# hazard-clean build: loop-edge rotation, DPP and v_cmp/v_cndmask wait states restored everywhere in hand-written code
# speedup vs baseline: 1.0075x; 1.0061x over previous
.Lpi0_ctx_att:
	s_and_b32 s48, s31, 0xff
	v_mov_b32_e32 v6, v232
	v_mul_hi_u32 v7, v6, s50
	v_lshrrev_b32_e32 v7, 6, v7
	v_mul_u32_u24_e32 v0, 0x120, v7
	v_sub_u32_e32 v6, v6, v0
	v_cmp_gt_u32_e32 vcc, 96, v6
	v_lshlrev_b32_e32 v0, 1, v6
	v_subrev_u32_e32 v2, 96, v6
	v_cndmask_b32_e32 v0, v2, v0, vcc
	v_cmp_lt_u32_e32 vcc, 0x5f, v0
	s_nop 1
	v_cndmask_b32_e64 v2, -1, 1, vcc
	v_mul_u32_u24_e32 v4, 0x900, v7
	v_lshl_add_u32 v4, v6, 3, v4
	global_load_dwordx2 v[58:59], v4, s[42:43]
	v_add_u32_e32 v5, 64, v2
	v_mad_u32_u24 v4, v5, s49, v4
	v_add_u32_e32 v5, s48, v7
	v_add_u32_e32 v5, v5, v2
	v_cmp_gt_u32_e32 vcc, 0x100, v5
	v_mov_b32_e32 v60, 0
	v_mov_b32_e32 v61, 0
	s_and_saveexec_b64 s[24:25], vcc
	global_load_dwordx2 v[60:61], v4, s[46:47]
	s_mov_b64 exec, s[24:25]
	v_add_u32_e32 v6, 0x200, v232
	v_mul_hi_u32 v7, v6, s50
	v_lshrrev_b32_e32 v7, 6, v7
	v_mul_u32_u24_e32 v0, 0x120, v7
	v_sub_u32_e32 v6, v6, v0
	v_cmp_gt_u32_e32 vcc, 96, v6
	v_lshlrev_b32_e32 v0, 1, v6
	v_subrev_u32_e32 v2, 96, v6
	v_cndmask_b32_e32 v0, v2, v0, vcc
	v_cmp_lt_u32_e32 vcc, 0x5f, v0
	s_nop 1
	v_cndmask_b32_e64 v2, -1, 1, vcc
	v_mul_u32_u24_e32 v4, 0x900, v7
	v_lshl_add_u32 v4, v6, 3, v4
	global_load_dwordx2 v[62:63], v4, s[42:43]
	v_add_u32_e32 v5, 64, v2
	v_mad_u32_u24 v4, v5, s49, v4
	v_add_u32_e32 v5, s48, v7
	v_add_u32_e32 v5, v5, v2
	v_cmp_gt_u32_e32 vcc, 0x100, v5
	v_mov_b32_e32 v64, 0
	v_mov_b32_e32 v65, 0
	s_and_saveexec_b64 s[24:25], vcc
	global_load_dwordx2 v[64:65], v4, s[46:47]
	s_mov_b64 exec, s[24:25]
	v_add_u32_e32 v6, 0x400, v232
	v_mul_hi_u32 v7, v6, s50
	v_lshrrev_b32_e32 v7, 6, v7
	v_mul_u32_u24_e32 v0, 0x120, v7
	v_sub_u32_e32 v6, v6, v0
	v_cmp_gt_u32_e32 vcc, 96, v6
	v_lshlrev_b32_e32 v0, 1, v6
	v_subrev_u32_e32 v2, 96, v6
	v_cndmask_b32_e32 v0, v2, v0, vcc
	v_cmp_lt_u32_e32 vcc, 0x5f, v0
	s_nop 1
	v_cndmask_b32_e64 v2, -1, 1, vcc
	v_mul_u32_u24_e32 v4, 0x900, v7
	v_lshl_add_u32 v4, v6, 3, v4
	global_load_dwordx2 v[66:67], v4, s[42:43]
	v_add_u32_e32 v5, 64, v2
	v_mad_u32_u24 v4, v5, s49, v4
	v_add_u32_e32 v5, s48, v7
	v_add_u32_e32 v5, v5, v2
	v_cmp_gt_u32_e32 vcc, 0x100, v5
	v_mov_b32_e32 v68, 0
	v_mov_b32_e32 v69, 0
	s_and_saveexec_b64 s[24:25], vcc
	global_load_dwordx2 v[68:69], v4, s[46:47]
	s_mov_b64 exec, s[24:25]
	v_add_u32_e32 v6, 0x600, v232
	v_mul_hi_u32 v7, v6, s50
	v_lshrrev_b32_e32 v7, 6, v7
	v_mul_u32_u24_e32 v0, 0x120, v7
	v_sub_u32_e32 v6, v6, v0
	v_cmp_gt_u32_e32 vcc, 96, v6
	v_lshlrev_b32_e32 v0, 1, v6
	v_subrev_u32_e32 v2, 96, v6
	v_cndmask_b32_e32 v0, v2, v0, vcc
	v_cmp_lt_u32_e32 vcc, 0x5f, v0
	s_nop 1
	v_cndmask_b32_e64 v2, -1, 1, vcc
	v_mul_u32_u24_e32 v4, 0x900, v7
	v_lshl_add_u32 v4, v6, 3, v4
	global_load_dwordx2 v[70:71], v4, s[42:43]
	v_add_u32_e32 v5, 64, v2
	v_mad_u32_u24 v4, v5, s49, v4
	v_add_u32_e32 v5, s48, v7
	v_add_u32_e32 v5, v5, v2
	v_cmp_gt_u32_e32 vcc, 0x100, v5
	v_mov_b32_e32 v72, 0
	v_mov_b32_e32 v73, 0
	s_and_saveexec_b64 s[24:25], vcc
	global_load_dwordx2 v[72:73], v4, s[46:47]
	s_mov_b64 exec, s[24:25]
	v_add_u32_e32 v6, 0x800, v232
	v_mul_hi_u32 v7, v6, s50
	v_lshrrev_b32_e32 v7, 6, v7
	v_mul_u32_u24_e32 v0, 0x120, v7
	v_sub_u32_e32 v6, v6, v0
	v_cmp_gt_u32_e32 vcc, 96, v6
	v_lshlrev_b32_e32 v0, 1, v6
	v_subrev_u32_e32 v2, 96, v6
	v_cndmask_b32_e32 v0, v2, v0, vcc
	v_cmp_lt_u32_e32 vcc, 0x5f, v0
	s_nop 1
	v_cndmask_b32_e64 v2, -1, 1, vcc
	v_mul_u32_u24_e32 v4, 0x900, v7
	v_lshl_add_u32 v4, v6, 3, v4
	global_load_dwordx2 v[74:75], v4, s[42:43]
	v_add_u32_e32 v5, 64, v2
	v_mad_u32_u24 v4, v5, s49, v4
	v_add_u32_e32 v5, s48, v7
	v_add_u32_e32 v5, v5, v2
	v_cmp_gt_u32_e32 vcc, 0x100, v5
	v_mov_b32_e32 v76, 0
	v_mov_b32_e32 v77, 0
	s_and_saveexec_b64 s[24:25], vcc
	global_load_dwordx2 v[76:77], v4, s[46:47]
	s_mov_b64 exec, s[24:25]
	v_add_u32_e32 v6, 0xa00, v232
	v_mul_hi_u32 v7, v6, s50
	v_lshrrev_b32_e32 v7, 6, v7
	v_mul_u32_u24_e32 v0, 0x120, v7
	v_sub_u32_e32 v6, v6, v0
	v_cmp_gt_u32_e32 vcc, 96, v6
	v_lshlrev_b32_e32 v0, 1, v6
	v_subrev_u32_e32 v2, 96, v6
	v_cndmask_b32_e32 v0, v2, v0, vcc
	v_cmp_lt_u32_e32 vcc, 0x5f, v0
	s_nop 1
	v_cndmask_b32_e64 v2, -1, 1, vcc
	v_mul_u32_u24_e32 v4, 0x900, v7
	v_lshl_add_u32 v4, v6, 3, v4
	global_load_dwordx2 v[78:79], v4, s[42:43]
	v_add_u32_e32 v5, 64, v2
	v_mad_u32_u24 v4, v5, s49, v4
	v_add_u32_e32 v5, s48, v7
	v_add_u32_e32 v5, v5, v2
	v_cmp_gt_u32_e32 vcc, 0x100, v5
	v_mov_b32_e32 v80, 0
	v_mov_b32_e32 v81, 0
	s_and_saveexec_b64 s[24:25], vcc
	global_load_dwordx2 v[80:81], v4, s[46:47]
	s_mov_b64 exec, s[24:25]
	v_add_u32_e32 v6, 0xc00, v232
	v_mul_hi_u32 v7, v6, s50
	v_lshrrev_b32_e32 v7, 6, v7
	v_mul_u32_u24_e32 v0, 0x120, v7
	v_sub_u32_e32 v6, v6, v0
	v_cmp_gt_u32_e32 vcc, 96, v6
	v_lshlrev_b32_e32 v0, 1, v6
	v_subrev_u32_e32 v2, 96, v6
	v_cndmask_b32_e32 v0, v2, v0, vcc
	v_cmp_lt_u32_e32 vcc, 0x5f, v0
	s_nop 1
	v_cndmask_b32_e64 v2, -1, 1, vcc
	v_mul_u32_u24_e32 v4, 0x900, v7
	v_lshl_add_u32 v4, v6, 3, v4
	global_load_dwordx2 v[82:83], v4, s[42:43]
	v_add_u32_e32 v5, 64, v2
	v_mad_u32_u24 v4, v5, s49, v4
	v_add_u32_e32 v5, s48, v7
	v_add_u32_e32 v5, v5, v2
	v_cmp_gt_u32_e32 vcc, 0x100, v5
	v_mov_b32_e32 v84, 0
	v_mov_b32_e32 v85, 0
	s_and_saveexec_b64 s[24:25], vcc
	global_load_dwordx2 v[84:85], v4, s[46:47]
	s_mov_b64 exec, s[24:25]
	v_add_u32_e32 v6, 0xe00, v232
	v_mul_hi_u32 v7, v6, s50
	v_lshrrev_b32_e32 v7, 6, v7
	v_mul_u32_u24_e32 v0, 0x120, v7
	v_sub_u32_e32 v6, v6, v0
	v_cmp_gt_u32_e32 vcc, 96, v6
	v_lshlrev_b32_e32 v0, 1, v6
	v_subrev_u32_e32 v2, 96, v6
	v_cndmask_b32_e32 v0, v2, v0, vcc
	v_cmp_lt_u32_e32 vcc, 0x5f, v0
	s_nop 1
	v_cndmask_b32_e64 v2, -1, 1, vcc
	v_mul_u32_u24_e32 v4, 0x900, v7
	v_lshl_add_u32 v4, v6, 3, v4
	global_load_dwordx2 v[86:87], v4, s[42:43]
	v_add_u32_e32 v5, 64, v2
	v_mad_u32_u24 v4, v5, s49, v4
	v_add_u32_e32 v5, s48, v7
	v_add_u32_e32 v5, v5, v2
	v_cmp_gt_u32_e32 vcc, 0x100, v5
	v_mov_b32_e32 v88, 0
	v_mov_b32_e32 v89, 0
	s_and_saveexec_b64 s[24:25], vcc
	global_load_dwordx2 v[88:89], v4, s[46:47]
	s_mov_b64 exec, s[24:25]
	v_add_u32_e32 v6, 0x1000, v232
	v_mul_hi_u32 v7, v6, s50
	v_lshrrev_b32_e32 v7, 6, v7
	v_mul_u32_u24_e32 v0, 0x120, v7
	v_sub_u32_e32 v6, v6, v0
	v_cmp_gt_u32_e32 vcc, 96, v6
	v_lshlrev_b32_e32 v0, 1, v6
	v_subrev_u32_e32 v2, 96, v6
	v_cndmask_b32_e32 v0, v2, v0, vcc
	v_cmp_lt_u32_e32 vcc, 0x5f, v0
	s_nop 1
	v_cndmask_b32_e64 v2, -1, 1, vcc
	v_mul_u32_u24_e32 v4, 0x900, v7
	v_lshl_add_u32 v4, v6, 3, v4
	global_load_dwordx2 v[90:91], v4, s[42:43]
	v_add_u32_e32 v5, 64, v2
	v_mad_u32_u24 v4, v5, s49, v4
	v_add_u32_e32 v5, s48, v7
	v_add_u32_e32 v5, v5, v2
	v_cmp_gt_u32_e32 vcc, 0x100, v5
	v_mov_b32_e32 v92, 0
	v_mov_b32_e32 v93, 0
	s_and_saveexec_b64 s[24:25], vcc
	global_load_dwordx2 v[92:93], v4, s[46:47]
	s_mov_b64 exec, s[24:25]

.Lpi_ctx:
	s_and_b32 s48, s72, 0xff
	v_cmp_gt_u32_e32 vcc, 96, v27
	v_lshlrev_b32_e32 v0, 1, v27
	v_subrev_u32_e32 v2, 96, v27
	v_cndmask_b32_e32 v0, v2, v0, vcc
	v_cmp_lt_u32_e32 vcc, 0x5f, v0
	s_nop 1
	v_cndmask_b32_e64 v2, -1, 1, vcc
	v_mul_u32_u24_e32 v4, 0x480, v29
	v_add_lshl_u32 v4, v4, v6, 1
	global_load_dwordx2 v[58:59], v4, s[42:43]
	v_add_u32_e32 v5, 64, v2
	v_mad_u32_u24 v4, v5, s49, v4
	v_add_u32_e32 v5, s48, v29
	v_add_u32_e32 v5, v5, v2
	v_cmp_gt_u32_e32 vcc, 0x100, v5
	v_mov_b32_e32 v60, 0
	v_mov_b32_e32 v61, 0
	s_and_saveexec_b64 s[26:27], vcc
	global_load_dwordx2 v[60:61], v4, s[46:47]
	s_mov_b64 exec, s[26:27]
	v_cmp_gt_u32_e32 vcc, 96, v28
	v_lshlrev_b32_e32 v0, 1, v28
	v_subrev_u32_e32 v2, 96, v28
	v_cndmask_b32_e32 v0, v2, v0, vcc
	v_cmp_lt_u32_e32 vcc, 0x5f, v0
	s_nop 1
	v_cndmask_b32_e64 v2, -1, 1, vcc
	v_mul_u32_u24_e32 v4, 0x480, v31
	v_add_lshl_u32 v4, v4, v8, 1
	global_load_dwordx2 v[62:63], v4, s[42:43]
	v_add_u32_e32 v5, 64, v2
	v_mad_u32_u24 v4, v5, s49, v4
	v_add_u32_e32 v5, s48, v31
	v_add_u32_e32 v5, v5, v2
	v_cmp_gt_u32_e32 vcc, 0x100, v5
	v_mov_b32_e32 v64, 0
	v_mov_b32_e32 v65, 0
	s_and_saveexec_b64 s[26:27], vcc
	global_load_dwordx2 v[64:65], v4, s[46:47]
	s_mov_b64 exec, s[26:27]
	v_cmp_gt_u32_e32 vcc, 96, v30
	v_lshlrev_b32_e32 v0, 1, v30
	v_subrev_u32_e32 v2, 96, v30
	v_cndmask_b32_e32 v0, v2, v0, vcc
	v_cmp_lt_u32_e32 vcc, 0x5f, v0
	s_nop 1
	v_cndmask_b32_e64 v2, -1, 1, vcc
	v_mul_u32_u24_e32 v4, 0x480, v33
	v_add_lshl_u32 v4, v4, v10, 1
	global_load_dwordx2 v[66:67], v4, s[42:43]
	v_add_u32_e32 v5, 64, v2
	v_mad_u32_u24 v4, v5, s49, v4
	v_add_u32_e32 v5, s48, v33
	v_add_u32_e32 v5, v5, v2
	v_cmp_gt_u32_e32 vcc, 0x100, v5
	v_mov_b32_e32 v68, 0
	v_mov_b32_e32 v69, 0
	s_and_saveexec_b64 s[26:27], vcc
	global_load_dwordx2 v[68:69], v4, s[46:47]
	s_mov_b64 exec, s[26:27]
	v_cmp_gt_u32_e32 vcc, 96, v32
	v_lshlrev_b32_e32 v0, 1, v32
	v_subrev_u32_e32 v2, 96, v32
	v_cndmask_b32_e32 v0, v2, v0, vcc
	v_cmp_lt_u32_e32 vcc, 0x5f, v0
	s_nop 1
	v_cndmask_b32_e64 v2, -1, 1, vcc
	v_mul_u32_u24_e32 v4, 0x480, v35
	v_add_lshl_u32 v4, v4, v12, 1
	global_load_dwordx2 v[70:71], v4, s[42:43]
	v_add_u32_e32 v5, 64, v2
	v_mad_u32_u24 v4, v5, s49, v4
	v_add_u32_e32 v5, s48, v35
	v_add_u32_e32 v5, v5, v2
	v_cmp_gt_u32_e32 vcc, 0x100, v5
	v_mov_b32_e32 v72, 0
	v_mov_b32_e32 v73, 0
	s_and_saveexec_b64 s[26:27], vcc
	global_load_dwordx2 v[72:73], v4, s[46:47]
	s_mov_b64 exec, s[26:27]
	v_cmp_gt_u32_e32 vcc, 96, v34
	v_lshlrev_b32_e32 v0, 1, v34
	v_subrev_u32_e32 v2, 96, v34
	v_cndmask_b32_e32 v0, v2, v0, vcc
	v_cmp_lt_u32_e32 vcc, 0x5f, v0
	s_nop 1
	v_cndmask_b32_e64 v2, -1, 1, vcc
	v_mul_u32_u24_e32 v4, 0x480, v37
	v_add_lshl_u32 v4, v4, v14, 1
	global_load_dwordx2 v[74:75], v4, s[42:43]
	v_add_u32_e32 v5, 64, v2
	v_mad_u32_u24 v4, v5, s49, v4
	v_add_u32_e32 v5, s48, v37
	v_add_u32_e32 v5, v5, v2
	v_cmp_gt_u32_e32 vcc, 0x100, v5
	v_mov_b32_e32 v76, 0
	v_mov_b32_e32 v77, 0
	s_and_saveexec_b64 s[26:27], vcc
	global_load_dwordx2 v[76:77], v4, s[46:47]
	s_mov_b64 exec, s[26:27]
	v_cmp_gt_u32_e32 vcc, 96, v36
	v_lshlrev_b32_e32 v0, 1, v36
	v_subrev_u32_e32 v2, 96, v36
	v_cndmask_b32_e32 v0, v2, v0, vcc
	v_cmp_lt_u32_e32 vcc, 0x5f, v0
	s_nop 1
	v_cndmask_b32_e64 v2, -1, 1, vcc
	v_mul_u32_u24_e32 v4, 0x480, v39
	v_add_lshl_u32 v4, v4, v16, 1
	global_load_dwordx2 v[78:79], v4, s[42:43]
	v_add_u32_e32 v5, 64, v2
	v_mad_u32_u24 v4, v5, s49, v4
	v_add_u32_e32 v5, s48, v39
	v_add_u32_e32 v5, v5, v2
	v_cmp_gt_u32_e32 vcc, 0x100, v5
	v_mov_b32_e32 v80, 0
	v_mov_b32_e32 v81, 0
	s_and_saveexec_b64 s[26:27], vcc
	global_load_dwordx2 v[80:81], v4, s[46:47]
	s_mov_b64 exec, s[26:27]
	v_cmp_gt_u32_e32 vcc, 96, v38
	v_lshlrev_b32_e32 v0, 1, v38
	v_subrev_u32_e32 v2, 96, v38
	v_cndmask_b32_e32 v0, v2, v0, vcc
	v_cmp_lt_u32_e32 vcc, 0x5f, v0
	s_nop 1
	v_cndmask_b32_e64 v2, -1, 1, vcc
	v_mul_u32_u24_e32 v4, 0x480, v41
	v_add_lshl_u32 v4, v4, v18, 1
	global_load_dwordx2 v[82:83], v4, s[42:43]
	v_add_u32_e32 v5, 64, v2
	v_mad_u32_u24 v4, v5, s49, v4
	v_add_u32_e32 v5, s48, v41
	v_add_u32_e32 v5, v5, v2
	v_cmp_gt_u32_e32 vcc, 0x100, v5
	v_mov_b32_e32 v84, 0
	v_mov_b32_e32 v85, 0
	s_and_saveexec_b64 s[26:27], vcc
	global_load_dwordx2 v[84:85], v4, s[46:47]
	s_mov_b64 exec, s[26:27]
	v_cmp_gt_u32_e32 vcc, 96, v40
	v_lshlrev_b32_e32 v0, 1, v40
	v_subrev_u32_e32 v2, 96, v40
	v_cndmask_b32_e32 v0, v2, v0, vcc
	v_cmp_lt_u32_e32 vcc, 0x5f, v0
	s_nop 1
	v_cndmask_b32_e64 v2, -1, 1, vcc
	v_mul_u32_u24_e32 v4, 0x480, v43
	v_add_lshl_u32 v4, v4, v20, 1
	global_load_dwordx2 v[86:87], v4, s[42:43]
	v_add_u32_e32 v5, 64, v2
	v_mad_u32_u24 v4, v5, s49, v4
	v_add_u32_e32 v5, s48, v43
	v_add_u32_e32 v5, v5, v2
	v_cmp_gt_u32_e32 vcc, 0x100, v5
	v_mov_b32_e32 v88, 0
	v_mov_b32_e32 v89, 0
	s_and_saveexec_b64 s[26:27], vcc
	global_load_dwordx2 v[88:89], v4, s[46:47]
	s_mov_b64 exec, s[26:27]
	v_cmp_gt_u32_e32 vcc, 96, v42
	v_lshlrev_b32_e32 v0, 1, v42
	v_subrev_u32_e32 v2, 96, v42
	v_cndmask_b32_e32 v0, v2, v0, vcc
	v_cmp_lt_u32_e32 vcc, 0x5f, v0
	s_nop 1
	v_cndmask_b32_e64 v2, -1, 1, vcc
	v_mul_u32_u24_e32 v4, 0x480, v45
	v_add_lshl_u32 v4, v4, v22, 1
	global_load_dwordx2 v[90:91], v4, s[42:43]
	v_add_u32_e32 v5, 64, v2
	v_mad_u32_u24 v4, v5, s49, v4
	v_add_u32_e32 v5, s48, v45
	v_add_u32_e32 v5, v5, v2
	v_cmp_gt_u32_e32 vcc, 0x100, v5
	v_mov_b32_e32 v92, 0
	v_mov_b32_e32 v93, 0
	s_and_saveexec_b64 s[26:27], vcc
	global_load_dwordx2 v[92:93], v4, s[46:47]
	s_mov_b64 exec, s[26:27]
